# in-proj 13th-tile MFMA skip dropped (its scalar test sat on every cluster's path); duplicate waits removed in the in-proj loops too
# baseline (speedup 1.0000x reference)
; #define PG8_STAGE(bufoff, gbase, voff) do { _Pragma("unroll") for (int _i = 0; _i < 2; ++_i) \
;         __builtin_amdgcn_global_load_lds((const unsigned*)((const char*)(gbase) + (voff)[_i]), (LAS unsigned*)(lds + (bufoff) + ldsw + _i * 8192), 16, 0, 0); } while (0)
; #define PG8_LDA(dst, b, h) do { _Pragma("unroll") for (int m = 0; m < 4; ++m) _Pragma("unroll") for (int k = 0; k < 2; ++k) dst[m][k] = *(const LAS bf16x8*)(lds + PG8_SA(b, h) + aoff + m * 2048 + k * 1024); } while (0)
; #define PG8_LDB(dst, b, h) do { _Pragma("unroll") for (int n = 0; n < 2; ++n) _Pragma("unroll") for (int k = 0; k < 2; ++k) dst[n][k] = *(const LAS bf16x8*)(lds + PG8_SB(b, h) + boff + n * 2048 + k * 1024); } while (0)
; #define PG8_MMA(ai, bj, At, Bt) do { __builtin_amdgcn_s_setprio(1); _Pragma("unroll") for (int m = 0; m < 4; ++m) _Pragma("unroll") for (int n = 0; n < 2; ++n) _Pragma("unroll") for (int k = 0; k < 2; ++k) \
;         acc[ai][bj][m][n] = __builtin_amdgcn_mfma_f32_16x16x32_bf16(Bt[n][k], At[m][k], acc[ai][bj][m][n], 0, 0, 0); __builtin_amdgcn_s_setprio(0); } while (0)
; #define PG8_WAIT_V(n) asm volatile("s_waitcnt vmcnt(" #n ")" ::: "memory")
; #define PG8_WAIT_L(n) asm volatile("s_waitcnt lgkmcnt(" #n ")" ::: "memory")
; #define PG8_BAR __builtin_amdgcn_s_barrier()
; #define PG8_SCHED __builtin_amdgcn_sched_barrier(0)
; template <class Epi>
; DEVI void gemm_phase(LAS unsigned char* lds, const Gemm g, const Epi& E) {
;     ...
;             const bool last = (t == nt - 2);
;             const char* a1 = cA + (size_t)(t + 1) * kstep;
;             const char* a2 = last ? nA : cA + (size_t)(t + 2) * kstep; const char* b2 = last ? nB : cB + (size_t)(t + 2) * kstep;
;             const char* a3 = a2 + kstep; const char* b3 = b2 + kstep;
;             PG8_LDB(B0, 0, 0); PG8_SCHED; PG8_LDA(At, 0, 0); PG8_STAGE(PG8_SA(1, 1), a1 + hstepA, voffA);
;             PG8_WAIT_L(8); PG8_BAR; PG8_WAIT_L(0); PG8_MMA(0, 0, At, B0); PG8_BAR; PG8_SCHED;
;             PG8_LDB(B1, 0, 1); PG8_STAGE(PG8_SB(0, 0), b2, voffB);
;             PG8_BAR; PG8_WAIT_L(0); PG8_MMA(0, 1, At, B1); PG8_BAR;
;             PG8_LDA(At, 0, 1); PG8_STAGE(PG8_SA(0, 0), a2, voffA);
;             PG8_BAR; PG8_WAIT_L(0); PG8_MMA(1, 0, At, B0); PG8_BAR; PG8_SCHED;
;             PG8_STAGE(PG8_SB(0, 1), b2 + hstepB, voffB);
;             PG8_WAIT_V(6); PG8_BAR; PG8_MMA(1, 1, At, B1); PG8_BAR;
.LBB0_276:
	s_add_u32 s19, s8, 0xfffc0080
	s_addc_u32 s26, s9, -1
	s_add_i32 s27, 0, 0x10000
	v_add_u32_e32 v8, s27, v214
	ds_read_b128 v[130:133], v8
	ds_read_b128 v[134:137], v8 offset:1024
	ds_read_b128 v[138:141], v8 offset:2048
	ds_read_b128 v[142:145], v8 offset:3072
	s_cmp_eq_u32 s18, 12
	s_cselect_b32 s69, s0, s26
	s_cselect_b32 s68, s1, s19
	s_cselect_b32 s47, s5, s15
	s_cselect_b32 s46, s7, s13
	v_lshl_add_u64 v[208:209], s[8:9], 0, v[184:185]
	s_add_i32 m0, s81, 0xc000
	ds_read_b128 v[146:149], v216
	ds_read_b128 v[150:153], v216 offset:1024
	ds_read_b128 v[188:191], v216 offset:2048
	ds_read_b128 v[192:195], v216 offset:3072
	ds_read_b128 v[196:199], v216 offset:4096
	ds_read_b128 v[200:203], v216 offset:5120
	ds_read_b128 v[204:207], v216 offset:6144
	ds_read_b128 v[218:221], v216 offset:7168
	global_load_lds_dwordx4 v[208:209], off
	s_add_i32 m0, s81, 0xe000
	v_lshl_add_u64 v[208:209], s[8:9], 0, v[186:187]
	global_load_lds_dwordx4 v[208:209], off
	s_waitcnt lgkmcnt(8)
	s_barrier
	s_waitcnt lgkmcnt(0)
	v_mfma_f32_16x16x32_bf16 v[126:129], v[130:133], v[146:149], v[126:129]
	v_mfma_f32_16x16x32_bf16 v[122:125], v[138:141], v[146:149], v[122:125]
	v_mfma_f32_16x16x32_bf16 v[114:117], v[130:133], v[188:191], v[114:117]
	v_mfma_f32_16x16x32_bf16 v[106:109], v[138:141], v[188:191], v[106:109]
	v_mfma_f32_16x16x32_bf16 v[94:97], v[130:133], v[196:199], v[94:97]
	v_mfma_f32_16x16x32_bf16 v[90:93], v[138:141], v[196:199], v[90:93]
	v_mfma_f32_16x16x32_bf16 v[82:85], v[130:133], v[204:207], v[82:85]
	v_mfma_f32_16x16x32_bf16 v[74:77], v[138:141], v[204:207], v[74:77]
	v_mfma_f32_16x16x32_bf16 v[126:129], v[134:137], v[150:153], v[126:129]
	v_mfma_f32_16x16x32_bf16 v[122:125], v[142:145], v[150:153], v[122:125]
	v_mfma_f32_16x16x32_bf16 v[114:117], v[134:137], v[192:195], v[114:117]
	v_mfma_f32_16x16x32_bf16 v[106:109], v[142:145], v[192:195], v[106:109]
	v_mfma_f32_16x16x32_bf16 v[94:97], v[134:137], v[200:203], v[94:97]
	v_mfma_f32_16x16x32_bf16 v[90:93], v[142:145], v[200:203], v[90:93]
	v_mfma_f32_16x16x32_bf16 v[82:85], v[134:137], v[218:221], v[82:85]
	v_mfma_f32_16x16x32_bf16 v[74:77], v[142:145], v[218:221], v[74:77]
	s_barrier
	s_add_i32 s19, 0, 0x14000
	s_add_i32 s26, s27, s80
	v_add_u32_e32 v8, s19, v214
	v_lshl_add_u64 v[208:209], s[46:47], 0, v[178:179]
	s_mov_b32 m0, s26
	ds_read_b128 v[222:225], v8
	ds_read_b128 v[226:229], v8 offset:1024
	ds_read_b128 v[230:233], v8 offset:2048
	ds_read_b128 v[234:237], v8 offset:3072
	global_load_lds_dwordx4 v[208:209], off
	s_add_i32 m0, s26, 0x2000
	v_lshl_add_u64 v[238:239], s[46:47], 0, v[182:183]
	global_load_lds_dwordx4 v[238:239], off
	s_barrier
	s_waitcnt lgkmcnt(0)
	v_mfma_f32_16x16x32_bf16 v[118:121], v[222:225], v[146:149], v[118:121]
	v_mfma_f32_16x16x32_bf16 v[110:113], v[230:233], v[146:149], v[110:113]
	v_mfma_f32_16x16x32_bf16 v[102:105], v[222:225], v[188:191], v[102:105]
	v_mfma_f32_16x16x32_bf16 v[98:101], v[230:233], v[188:191], v[98:101]
	v_mfma_f32_16x16x32_bf16 v[86:89], v[222:225], v[196:199], v[86:89]
	v_mfma_f32_16x16x32_bf16 v[78:81], v[230:233], v[196:199], v[78:81]
	v_mfma_f32_16x16x32_bf16 v[62:65], v[222:225], v[204:207], v[62:65]
	v_mfma_f32_16x16x32_bf16 v[58:61], v[230:233], v[204:207], v[58:61]
	v_mfma_f32_16x16x32_bf16 v[118:121], v[226:229], v[150:153], v[118:121]
	v_mfma_f32_16x16x32_bf16 v[110:113], v[234:237], v[150:153], v[110:113]
	v_mfma_f32_16x16x32_bf16 v[102:105], v[226:229], v[192:195], v[102:105]
	v_mfma_f32_16x16x32_bf16 v[98:101], v[234:237], v[192:195], v[98:101]
	v_mfma_f32_16x16x32_bf16 v[86:89], v[226:229], v[200:203], v[86:89]
	v_mfma_f32_16x16x32_bf16 v[78:81], v[234:237], v[200:203], v[78:81]
	v_mfma_f32_16x16x32_bf16 v[62:65], v[226:229], v[218:221], v[62:65]
	v_mfma_f32_16x16x32_bf16 v[58:61], v[234:237], v[218:221], v[58:61]
	s_mov_b32 m0, s81
	v_lshl_add_u64 v[240:241], s[68:69], 0, v[176:177]
	s_barrier
	ds_read_b128 v[146:149], v216 offset:16384
	ds_read_b128 v[150:153], v216 offset:17408
	ds_read_b128 v[188:191], v216 offset:18432
	ds_read_b128 v[192:195], v216 offset:19456
	ds_read_b128 v[196:199], v216 offset:20480
	ds_read_b128 v[200:203], v216 offset:21504
	ds_read_b128 v[204:207], v216 offset:22528
	ds_read_b128 v[218:221], v216 offset:23552
	global_load_lds_dwordx4 v[240:241], off
	s_mov_b32 m0, s82
	v_lshl_add_u64 v[242:243], s[68:69], 0, v[180:181]
	global_load_lds_dwordx4 v[242:243], off
	s_barrier
	s_waitcnt lgkmcnt(0)
	v_mfma_f32_16x16x32_bf16 v[70:73], v[130:133], v[146:149], v[70:73]
	v_mfma_f32_16x16x32_bf16 v[66:69], v[138:141], v[146:149], v[66:69]
	v_mfma_f32_16x16x32_bf16 v[46:49], v[130:133], v[188:191], v[46:49]
	v_mfma_f32_16x16x32_bf16 v[42:45], v[138:141], v[188:191], v[42:45]
	v_mfma_f32_16x16x32_bf16 v[30:33], v[130:133], v[196:199], v[30:33]
	v_mfma_f32_16x16x32_bf16 v[26:29], v[138:141], v[196:199], v[26:29]
	v_mfma_f32_16x16x32_bf16 v[14:17], v[130:133], v[204:207], v[14:17]
	v_mfma_f32_16x16x32_bf16 v[10:13], v[138:141], v[204:207], v[10:13]
	v_mfma_f32_16x16x32_bf16 v[70:73], v[134:137], v[150:153], v[70:73]
	v_mfma_f32_16x16x32_bf16 v[66:69], v[142:145], v[150:153], v[66:69]
	v_mfma_f32_16x16x32_bf16 v[46:49], v[134:137], v[192:195], v[46:49]
	v_mfma_f32_16x16x32_bf16 v[42:45], v[142:145], v[192:195], v[42:45]
	v_mfma_f32_16x16x32_bf16 v[30:33], v[134:137], v[200:203], v[30:33]
	v_mfma_f32_16x16x32_bf16 v[26:29], v[142:145], v[200:203], v[26:29]
	v_mfma_f32_16x16x32_bf16 v[14:17], v[134:137], v[218:221], v[14:17]
	v_mfma_f32_16x16x32_bf16 v[10:13], v[142:145], v[218:221], v[10:13]
	s_barrier
; #define PG8_STAGE(bufoff, gbase, voff) do { _Pragma("unroll") for (int _i = 0; _i < 2; ++_i) \
;         __builtin_amdgcn_global_load_lds((const unsigned*)((const char*)(gbase) + (voff)[_i]), (LAS unsigned*)(lds + (bufoff) + ldsw + _i * 8192), 16, 0, 0); } while (0)
; #define PG8_LDA(dst, b, h) do { _Pragma("unroll") for (int m = 0; m < 4; ++m) _Pragma("unroll") for (int k = 0; k < 2; ++k) dst[m][k] = *(const LAS bf16x8*)(lds + PG8_SA(b, h) + aoff + m * 2048 + k * 1024); } while (0)
; #define PG8_LDB(dst, b, h) do { _Pragma("unroll") for (int n = 0; n < 2; ++n) _Pragma("unroll") for (int k = 0; k < 2; ++k) dst[n][k] = *(const LAS bf16x8*)(lds + PG8_SB(b, h) + boff + n * 2048 + k * 1024); } while (0)
; #define PG8_MMA(ai, bj, At, Bt) do { __builtin_amdgcn_s_setprio(1); _Pragma("unroll") for (int m = 0; m < 4; ++m) _Pragma("unroll") for (int n = 0; n < 2; ++n) _Pragma("unroll") for (int k = 0; k < 2; ++k) \
;         acc[ai][bj][m][n] = __builtin_amdgcn_mfma_f32_16x16x32_bf16(Bt[n][k], At[m][k], acc[ai][bj][m][n], 0, 0, 0); __builtin_amdgcn_s_setprio(0); } while (0)
; #define PG8_WAIT_V(n) asm volatile("s_waitcnt vmcnt(" #n ")" ::: "memory")
; #define PG8_WAIT_L(n) asm volatile("s_waitcnt lgkmcnt(" #n ")" ::: "memory")
; #define PG8_BAR __builtin_amdgcn_s_barrier()
; #define PG8_SCHED __builtin_amdgcn_sched_barrier(0)
; template <class Epi>
; DEVI void gemm_phase(LAS unsigned char* lds, const Gemm g, const Epi& E) {
;     ...
;             PG8_WAIT_V(6); PG8_BAR; PG8_MMA(1, 1, At, B1); PG8_BAR;
;             PG8_LDB(B0, 1, 0); PG8_SCHED; PG8_LDA(At, 1, 0); PG8_STAGE(PG8_SA(0, 1), a2 + hstepA, voffA);
;             PG8_WAIT_L(8); PG8_BAR; PG8_WAIT_L(0); PG8_MMA(0, 0, At, B0); PG8_BAR; PG8_SCHED;
;             PG8_LDB(B1, 1, 1); PG8_STAGE(PG8_SB(1, 0), b3, voffB);
;             PG8_BAR; PG8_WAIT_L(0); PG8_MMA(0, 1, At, B1); PG8_BAR;
;             PG8_LDA(At, 1, 1); PG8_STAGE(PG8_SA(1, 0), a3, voffA);
;             PG8_BAR; PG8_WAIT_L(0); PG8_MMA(1, 0, At, B0); PG8_BAR; PG8_SCHED;
;             PG8_STAGE(PG8_SB(1, 1), b3 + hstepB, voffB);
	s_add_u32 s26, s46, 0x40000
	s_addc_u32 s27, s47, 0
	s_add_i32 s19, s19, s80
	s_mov_b32 m0, s19
	v_lshl_add_u64 v[130:131], s[26:27], 0, v[178:179]
	global_load_lds_dwordx4 v[130:131], off
	s_add_i32 m0, s19, 0x2000
	v_lshl_add_u64 v[130:131], s[26:27], 0, v[182:183]
	global_load_lds_dwordx4 v[130:131], off
	s_waitcnt vmcnt(6)
	s_barrier
	v_mfma_f32_16x16x32_bf16 v[50:53], v[222:225], v[146:149], v[50:53]
	v_mfma_f32_16x16x32_bf16 v[54:57], v[230:233], v[146:149], v[54:57]
	v_mfma_f32_16x16x32_bf16 v[34:37], v[222:225], v[188:191], v[34:37]
	v_mfma_f32_16x16x32_bf16 v[38:41], v[230:233], v[188:191], v[38:41]
	v_mfma_f32_16x16x32_bf16 v[18:21], v[222:225], v[196:199], v[18:21]
	v_mfma_f32_16x16x32_bf16 v[22:25], v[230:233], v[196:199], v[22:25]
	v_mfma_f32_16x16x32_bf16 v[0:3], v[222:225], v[204:207], v[0:3]
	v_mfma_f32_16x16x32_bf16 v[4:7], v[230:233], v[204:207], v[4:7]
	v_mfma_f32_16x16x32_bf16 v[50:53], v[226:229], v[150:153], v[50:53]
	v_mfma_f32_16x16x32_bf16 v[54:57], v[234:237], v[150:153], v[54:57]
	v_mfma_f32_16x16x32_bf16 v[34:37], v[226:229], v[192:195], v[34:37]
	v_mfma_f32_16x16x32_bf16 v[38:41], v[234:237], v[192:195], v[38:41]
	v_mfma_f32_16x16x32_bf16 v[18:21], v[226:229], v[200:203], v[18:21]
	v_mfma_f32_16x16x32_bf16 v[22:25], v[234:237], v[200:203], v[22:25]
	v_mfma_f32_16x16x32_bf16 v[0:3], v[226:229], v[218:221], v[0:3]
	v_mfma_f32_16x16x32_bf16 v[4:7], v[234:237], v[218:221], v[4:7]
	s_add_i32 s19, 0, 0x18000
	v_add_u32_e32 v8, s19, v214
	s_barrier
	ds_read_b128 v[130:133], v8
	ds_read_b128 v[134:137], v8 offset:1024
	ds_read_b128 v[138:141], v8 offset:2048
	ds_read_b128 v[142:145], v8 offset:3072
	s_add_u32 s26, s68, 0x40000
	s_addc_u32 s27, s69, 0
	s_mov_b32 m0, s83
	v_lshl_add_u64 v[222:223], s[26:27], 0, v[176:177]
	ds_read_b128 v[146:149], v216 offset:32768
	ds_read_b128 v[150:153], v216 offset:33792
	ds_read_b128 v[188:191], v216 offset:34816
	ds_read_b128 v[192:195], v216 offset:35840
	ds_read_b128 v[196:199], v216 offset:36864
	ds_read_b128 v[200:203], v216 offset:37888
	ds_read_b128 v[204:207], v216 offset:38912
	ds_read_b128 v[218:221], v216 offset:39936
	global_load_lds_dwordx4 v[222:223], off
	s_mov_b32 m0, s84
	v_lshl_add_u64 v[222:223], s[26:27], 0, v[180:181]
	global_load_lds_dwordx4 v[222:223], off
	s_waitcnt lgkmcnt(8)
	s_barrier
	s_waitcnt lgkmcnt(0)
	v_mfma_f32_16x16x32_bf16 v[126:129], v[130:133], v[146:149], v[126:129]
	v_mfma_f32_16x16x32_bf16 v[122:125], v[138:141], v[146:149], v[122:125]
	v_mfma_f32_16x16x32_bf16 v[114:117], v[130:133], v[188:191], v[114:117]
	v_mfma_f32_16x16x32_bf16 v[106:109], v[138:141], v[188:191], v[106:109]
	v_mfma_f32_16x16x32_bf16 v[94:97], v[130:133], v[196:199], v[94:97]
	v_mfma_f32_16x16x32_bf16 v[90:93], v[138:141], v[196:199], v[90:93]
	v_mfma_f32_16x16x32_bf16 v[82:85], v[130:133], v[204:207], v[82:85]
	v_mfma_f32_16x16x32_bf16 v[74:77], v[138:141], v[204:207], v[74:77]
	v_mfma_f32_16x16x32_bf16 v[126:129], v[134:137], v[150:153], v[126:129]
	v_mfma_f32_16x16x32_bf16 v[122:125], v[142:145], v[150:153], v[122:125]
	v_mfma_f32_16x16x32_bf16 v[114:117], v[134:137], v[192:195], v[114:117]
	v_mfma_f32_16x16x32_bf16 v[106:109], v[142:145], v[192:195], v[106:109]
	v_mfma_f32_16x16x32_bf16 v[94:97], v[134:137], v[200:203], v[94:97]
	v_mfma_f32_16x16x32_bf16 v[90:93], v[142:145], v[200:203], v[90:93]
	v_mfma_f32_16x16x32_bf16 v[82:85], v[134:137], v[218:221], v[82:85]
	v_mfma_f32_16x16x32_bf16 v[74:77], v[142:145], v[218:221], v[74:77]
	s_barrier
	s_add_i32 s38, 0, 0x1c000
	s_add_i32 s19, s19, s80
	v_add_u32_e32 v8, s38, v214
	v_lshl_add_u64 v[208:209], v[208:209], 0, s[70:71]
	s_mov_b32 m0, s19
	ds_read_b128 v[222:225], v8
	ds_read_b128 v[226:229], v8 offset:1024
	ds_read_b128 v[230:233], v8 offset:2048
	ds_read_b128 v[234:237], v8 offset:3072
	global_load_lds_dwordx4 v[208:209], off
	s_add_i32 m0, s19, 0x2000
	v_lshl_add_u64 v[208:209], v[238:239], 0, s[70:71]
	global_load_lds_dwordx4 v[208:209], off
	s_barrier
	s_waitcnt lgkmcnt(0)
	v_mfma_f32_16x16x32_bf16 v[118:121], v[222:225], v[146:149], v[118:121]
	v_mfma_f32_16x16x32_bf16 v[110:113], v[230:233], v[146:149], v[110:113]
	v_mfma_f32_16x16x32_bf16 v[102:105], v[222:225], v[188:191], v[102:105]
	v_mfma_f32_16x16x32_bf16 v[98:101], v[230:233], v[188:191], v[98:101]
	v_mfma_f32_16x16x32_bf16 v[86:89], v[222:225], v[196:199], v[86:89]
	v_mfma_f32_16x16x32_bf16 v[78:81], v[230:233], v[196:199], v[78:81]
	v_mfma_f32_16x16x32_bf16 v[62:65], v[222:225], v[204:207], v[62:65]
	v_mfma_f32_16x16x32_bf16 v[58:61], v[230:233], v[204:207], v[58:61]
	v_mfma_f32_16x16x32_bf16 v[118:121], v[226:229], v[150:153], v[118:121]
	v_mfma_f32_16x16x32_bf16 v[110:113], v[234:237], v[150:153], v[110:113]
	v_mfma_f32_16x16x32_bf16 v[102:105], v[226:229], v[192:195], v[102:105]
	v_mfma_f32_16x16x32_bf16 v[98:101], v[234:237], v[192:195], v[98:101]
	v_mfma_f32_16x16x32_bf16 v[86:89], v[226:229], v[200:203], v[86:89]
	v_mfma_f32_16x16x32_bf16 v[78:81], v[234:237], v[200:203], v[78:81]
	v_mfma_f32_16x16x32_bf16 v[62:65], v[226:229], v[218:221], v[62:65]
	v_mfma_f32_16x16x32_bf16 v[58:61], v[234:237], v[218:221], v[58:61]
	s_mov_b32 m0, s85
	v_lshl_add_u64 v[208:209], v[240:241], 0, s[70:71]
	s_barrier
	ds_read_b128 v[146:149], v216 offset:49152
	ds_read_b128 v[150:153], v216 offset:50176
	ds_read_b128 v[188:191], v216 offset:51200
	ds_read_b128 v[192:195], v216 offset:52224
	ds_read_b128 v[196:199], v216 offset:53248
	ds_read_b128 v[200:203], v216 offset:54272
	ds_read_b128 v[204:207], v216 offset:55296
	ds_read_b128 v[218:221], v216 offset:56320
	global_load_lds_dwordx4 v[208:209], off
	s_mov_b32 m0, s86
	v_lshl_add_u64 v[208:209], v[242:243], 0, s[70:71]
	global_load_lds_dwordx4 v[208:209], off
	s_barrier
; #define PG8_STAGE(bufoff, gbase, voff) do { _Pragma("unroll") for (int _i = 0; _i < 2; ++_i) \
;         __builtin_amdgcn_global_load_lds((const unsigned*)((const char*)(gbase) + (voff)[_i]), (LAS unsigned*)(lds + (bufoff) + ldsw + _i * 8192), 16, 0, 0); } while (0)
; #define PG8_MMA(ai, bj, At, Bt) do { __builtin_amdgcn_s_setprio(1); _Pragma("unroll") for (int m = 0; m < 4; ++m) _Pragma("unroll") for (int n = 0; n < 2; ++n) _Pragma("unroll") for (int k = 0; k < 2; ++k) \
;         acc[ai][bj][m][n] = __builtin_amdgcn_mfma_f32_16x16x32_bf16(Bt[n][k], At[m][k], acc[ai][bj][m][n], 0, 0, 0); __builtin_amdgcn_s_setprio(0); } while (0)
; #define PG8_WAIT_V(n) asm volatile("s_waitcnt vmcnt(" #n ")" ::: "memory")
; #define PG8_BAR __builtin_amdgcn_s_barrier()
; template <class Epi>
; DEVI void gemm_phase(LAS unsigned char* lds, const Gemm g, const Epi& E) {
;     ...
;             PG8_STAGE(PG8_SB(1, 1), b3 + hstepB, voffB);
;             PG8_WAIT_V(6); PG8_BAR; PG8_MMA(1, 1, At, B1); PG8_BAR;
;         }
;     ...
;             const int row0 = cur.pm * BM + wr * 64 + fr, col0 = cur.pn * BM + wc * 32 + (Epi::PERM ? 8 : 4) * fq; constexpr int NST = Epi::PERM ? 4 : 16;
;             float rsv[8];
;             if constexpr (Epi::RS) { f32x4 q4[8];
; #pragma unroll
;                 for (int i = 0; i < 8; ++i) q4[i] = *(const f32x4*)(E.ssq_in + (size_t)(row0 + (i >> 2) * HALF + (i & 3) * 16) * 4);
; #pragma unroll
;                 for (int i = 0; i < 8; ++i) rsv[i] = rsqrtf((((q4[i][0] + q4[i][1]) + q4[i][2]) + q4[i][3]) * (1.f / DM) + 1e-6f); }
	s_waitcnt lgkmcnt(0)
	v_mfma_f32_16x16x32_bf16 v[70:73], v[130:133], v[146:149], v[70:73]
	v_mfma_f32_16x16x32_bf16 v[66:69], v[138:141], v[146:149], v[66:69]
	v_mfma_f32_16x16x32_bf16 v[46:49], v[130:133], v[188:191], v[46:49]
	v_mfma_f32_16x16x32_bf16 v[42:45], v[138:141], v[188:191], v[42:45]
	v_mfma_f32_16x16x32_bf16 v[30:33], v[130:133], v[196:199], v[30:33]
	v_mfma_f32_16x16x32_bf16 v[26:29], v[138:141], v[196:199], v[26:29]
	v_mfma_f32_16x16x32_bf16 v[14:17], v[130:133], v[204:207], v[14:17]
	v_mfma_f32_16x16x32_bf16 v[10:13], v[138:141], v[204:207], v[10:13]
	v_mfma_f32_16x16x32_bf16 v[70:73], v[134:137], v[150:153], v[70:73]
	v_mfma_f32_16x16x32_bf16 v[66:69], v[142:145], v[150:153], v[66:69]
	v_mfma_f32_16x16x32_bf16 v[46:49], v[134:137], v[192:195], v[46:49]
	v_mfma_f32_16x16x32_bf16 v[42:45], v[142:145], v[192:195], v[42:45]
	v_mfma_f32_16x16x32_bf16 v[30:33], v[134:137], v[200:203], v[30:33]
	v_mfma_f32_16x16x32_bf16 v[26:29], v[142:145], v[200:203], v[26:29]
	v_mfma_f32_16x16x32_bf16 v[14:17], v[134:137], v[218:221], v[14:17]
	v_mfma_f32_16x16x32_bf16 v[10:13], v[142:145], v[218:221], v[10:13]
	s_barrier
	s_add_u32 s26, s46, 0x40080
	s_addc_u32 s27, s47, 0
	s_add_i32 s19, s38, s80
	s_mov_b32 m0, s19
	v_lshl_add_u64 v[130:131], s[26:27], 0, v[178:179]
	global_load_lds_dwordx4 v[130:131], off
	s_add_i32 m0, s19, 0x2000
	v_lshl_add_u64 v[130:131], s[26:27], 0, v[182:183]
	global_load_lds_dwordx4 v[130:131], off
	s_waitcnt vmcnt(6)
	s_barrier
	v_mfma_f32_16x16x32_bf16 v[50:53], v[222:225], v[146:149], v[50:53]
	v_mfma_f32_16x16x32_bf16 v[54:57], v[230:233], v[146:149], v[54:57]
	v_mfma_f32_16x16x32_bf16 v[34:37], v[222:225], v[188:191], v[34:37]
	v_mfma_f32_16x16x32_bf16 v[38:41], v[230:233], v[188:191], v[38:41]
	v_mfma_f32_16x16x32_bf16 v[18:21], v[222:225], v[196:199], v[18:21]
	v_mfma_f32_16x16x32_bf16 v[22:25], v[230:233], v[196:199], v[22:25]
	v_mfma_f32_16x16x32_bf16 v[0:3], v[222:225], v[204:207], v[0:3]
	v_mfma_f32_16x16x32_bf16 v[4:7], v[230:233], v[204:207], v[4:7]
	v_mfma_f32_16x16x32_bf16 v[50:53], v[226:229], v[150:153], v[50:53]
	v_mfma_f32_16x16x32_bf16 v[54:57], v[234:237], v[150:153], v[54:57]
	v_mfma_f32_16x16x32_bf16 v[34:37], v[226:229], v[192:195], v[34:37]
	v_mfma_f32_16x16x32_bf16 v[38:41], v[234:237], v[192:195], v[38:41]
	v_mfma_f32_16x16x32_bf16 v[18:21], v[226:229], v[200:203], v[18:21]
	v_mfma_f32_16x16x32_bf16 v[22:25], v[234:237], v[200:203], v[22:25]
	v_mfma_f32_16x16x32_bf16 v[0:3], v[226:229], v[218:221], v[0:3]
	v_mfma_f32_16x16x32_bf16 v[4:7], v[234:237], v[218:221], v[4:7]
	s_add_i32 s18, s18, 2
	s_add_u32 s8, s8, 0x100
	s_addc_u32 s9, s9, 0
	s_add_u32 s13, s13, 0x100
	s_addc_u32 s15, s15, 0
	s_cmp_gt_u32 s18, 13
	s_barrier
	s_cbranch_scc0 .LBB0_276
	s_setprio 0
	v_lshl_add_u32 v204, s6, 8, v213
	v_add_u32_e32 v188, 0xb0, v204
	v_ashrrev_i32_e32 v205, 31, v204
	v_or_b32_e32 v202, 16, v204
	v_ashrrev_i32_e32 v189, 31, v188
	v_lshl_add_u64 v[130:131], v[204:205], 4, s[76:77]
	v_ashrrev_i32_e32 v203, 31, v202
	v_lshl_add_u64 v[134:135], v[188:189], 4, s[76:77]
	global_load_dwordx4 v[206:209], v[130:131], off
	v_or_b32_e32 v200, 32, v204
	global_load_dwordx4 v[134:137], v[134:135], off
	v_lshl_add_u64 v[130:131], v[202:203], 4, s[76:77]
	global_load_dwordx4 v[218:221], v[130:131], off
	v_ashrrev_i32_e32 v201, 31, v200
	v_or_b32_e32 v198, 48, v204
	v_lshl_add_u64 v[130:131], v[200:201], 4, s[76:77]
	v_ashrrev_i32_e32 v199, 31, v198
	v_add_u32_e32 v196, 0x80, v204
	global_load_dwordx4 v[146:149], v[130:131], off
	v_lshl_add_u64 v[130:131], v[198:199], 4, s[76:77]
	v_ashrrev_i32_e32 v197, 31, v196
	v_add_u32_e32 v194, 0x90, v204
	global_load_dwordx4 v[150:153], v[130:131], off
	v_lshl_add_u64 v[130:131], v[196:197], 4, s[76:77]
	v_ashrrev_i32_e32 v195, 31, v194
	v_add_u32_e32 v192, 0xa0, v204
	global_load_dwordx4 v[138:141], v[130:131], off
	v_lshl_add_u64 v[130:131], v[194:195], 4, s[76:77]
	v_ashrrev_i32_e32 v193, 31, v192
	global_load_dwordx4 v[142:145], v[130:131], off
	v_lshl_add_u64 v[130:131], v[192:193], 4, s[76:77]
	global_load_dwordx4 v[130:133], v[130:131], off
	s_waitcnt vmcnt(0)
	v_mov_b32_e32 v191, v206
	v_mov_b32_e32 v190, v218
	v_mov_b32_e32 v206, v219
	v_pk_add_f32 v[190:191], v[190:191], v[206:207]
	v_mov_b32_e32 v206, v220
	v_mov_b32_e32 v207, v208
	v_pk_add_f32 v[190:191], v[206:207], v[190:191]
	v_mov_b32_e32 v208, v221
	v_pk_add_f32 v[190:191], v[208:209], v[190:191]
	s_nop 0
	v_pk_fma_f32 v[206:207], v[190:191], s[72:73], v[160:161] op_sel_hi:[1,0,0]
	v_lshl_or_b32 v190, s4, 8, v215
	v_mul_f32_e32 v8, 0x4b800000, v207
	v_cmp_gt_f32_e32 vcc, s94, v207
	v_cmp_gt_f32_e64 s[6:7], s94, v206
	s_nop 0
	v_cndmask_b32_e32 v8, v207, v8, vcc
	v_rsq_f32_e32 v8, v8
	s_nop 0
	v_mul_f32_e32 v162, 0x45800000, v8
	v_cndmask_b32_e32 v208, v8, v162, vcc
	v_pk_mul_f32 v[128:129], v[128:129], v[208:209] op_sel_hi:[1,0]
	v_pk_mul_f32 v[126:127], v[126:127], v[208:209] op_sel_hi:[1,0]
	v_pk_mul_f32 v[124:125], v[124:125], v[208:209] op_sel_hi:[1,0]
	v_pk_mul_f32 v[122:123], v[122:123], v[208:209] op_sel_hi:[1,0]
	v_cmp_lt_i32_e32 vcc, s39, v190
	v_add_u32_e32 v8, 0xfffff400, v190
	s_and_saveexec_b64 s[0:1], vcc
	s_xor_b64 s[8:9], exec, s[0:1]
	s_cbranch_execz .LBB0_281
	v_cmp_gt_u32_e64 s[4:5], 16, v8
	s_and_saveexec_b64 s[46:47], s[4:5]
	s_cbranch_execz .LBB0_280
	v_lshlrev_b64 v[218:219], 6, v[204:205]
	v_lshl_add_u64 v[218:219], s[58:59], 0, v[218:219]
	v_lshl_add_u64 v[218:219], v[8:9], 2, v[218:219]
	global_store_dwordx4 v[218:219], v[126:129], off
	global_store_dwordx4 v[218:219], v[122:125], off offset:16

; #define PG8_STAGE(bufoff, gbase, voff) do { _Pragma("unroll") for (int _i = 0; _i < 2; ++_i) \
;         __builtin_amdgcn_global_load_lds((const unsigned*)((const char*)(gbase) + (voff)[_i]), (LAS unsigned*)(lds + (bufoff) + ldsw + _i * 8192), 16, 0, 0); } while (0)
; #define PG8_LDA(dst, b, h) do { _Pragma("unroll") for (int m = 0; m < 4; ++m) _Pragma("unroll") for (int k = 0; k < 2; ++k) dst[m][k] = *(const LAS bf16x8*)(lds + PG8_SA(b, h) + aoff + m * 2048 + k * 1024); } while (0)
; #define PG8_LDB(dst, b, h) do { _Pragma("unroll") for (int n = 0; n < 2; ++n) _Pragma("unroll") for (int k = 0; k < 2; ++k) dst[n][k] = *(const LAS bf16x8*)(lds + PG8_SB(b, h) + boff + n * 2048 + k * 1024); } while (0)
; #define PG8_MMA(ai, bj, At, Bt) do { __builtin_amdgcn_s_setprio(1); _Pragma("unroll") for (int m = 0; m < 4; ++m) _Pragma("unroll") for (int n = 0; n < 2; ++n) _Pragma("unroll") for (int k = 0; k < 2; ++k) \
;         acc[ai][bj][m][n] = __builtin_amdgcn_mfma_f32_16x16x32_bf16(Bt[n][k], At[m][k], acc[ai][bj][m][n], 0, 0, 0); __builtin_amdgcn_s_setprio(0); } while (0)
; #define PG8_WAIT_V(n) asm volatile("s_waitcnt vmcnt(" #n ")" ::: "memory")
; #define PG8_WAIT_L(n) asm volatile("s_waitcnt lgkmcnt(" #n ")" ::: "memory")
; #define PG8_BAR __builtin_amdgcn_s_barrier()
; template <class Epi>
; DEVI void gemm_phase(LAS unsigned char* lds, const Gemm g, const Epi& E) {
;     ...
;         for (int t = 0; t < nt; t += 2) {
;             const bool last = (t == nt - 2);
;             const char* a1 = cA + (size_t)(t + 1) * kstep;
;             const char* a2 = last ? nA : cA + (size_t)(t + 2) * kstep; const char* b2 = last ? nB : cB + (size_t)(t + 2) * kstep;
;             const char* a3 = a2 + kstep; const char* b3 = b2 + kstep;
;             PG8_LDB(B0, 0, 0); PG8_SCHED; PG8_LDA(At, 0, 0); PG8_STAGE(PG8_SA(1, 1), a1 + hstepA, voffA);
;             PG8_WAIT_L(8); PG8_BAR; PG8_WAIT_L(0); PG8_MMA(0, 0, At, B0); PG8_BAR; PG8_SCHED;
;             PG8_LDB(B1, 0, 1); PG8_STAGE(PG8_SB(0, 0), b2, voffB);
;             PG8_BAR; PG8_WAIT_L(0); PG8_MMA(0, 1, At, B1); PG8_BAR;
;             PG8_LDA(At, 0, 1); PG8_STAGE(PG8_SA(0, 0), a2, voffA);
;             PG8_BAR; PG8_WAIT_L(0); PG8_MMA(1, 0, At, B0); PG8_BAR; PG8_SCHED;
;             PG8_STAGE(PG8_SB(0, 1), b2 + hstepB, voffB);
;             PG8_WAIT_V(6); PG8_BAR; PG8_MMA(1, 1, At, B1); PG8_BAR;
.LBB0_356:
	s_add_u32 s19, s8, 0xfffc0080
	s_addc_u32 s26, s9, -1
	s_add_i32 s27, 0, 0x10000
	v_add_u32_e32 v142, s27, v209
	ds_read_b128 v[130:133], v142
	ds_read_b128 v[134:137], v142 offset:1024
	ds_read_b128 v[138:141], v142 offset:2048
	ds_read_b128 v[142:145], v142 offset:3072
	s_cmp_eq_u32 s18, 12
	s_cselect_b32 s69, s0, s26
	s_cselect_b32 s68, s1, s19
	s_cselect_b32 s47, s5, s13
	s_cselect_b32 s46, s7, s11
	v_lshl_add_u64 v[206:207], s[8:9], 0, v[182:183]
	s_add_i32 m0, s85, 0xc000
	ds_read_b128 v[146:149], v214
	ds_read_b128 v[150:153], v214 offset:1024
	ds_read_b128 v[186:189], v214 offset:2048
	ds_read_b128 v[190:193], v214 offset:3072
	ds_read_b128 v[194:197], v214 offset:4096
	ds_read_b128 v[198:201], v214 offset:5120
	ds_read_b128 v[202:205], v214 offset:6144
	ds_read_b128 v[216:219], v214 offset:7168
	global_load_lds_dwordx4 v[206:207], off
	s_add_i32 m0, s85, 0xe000
	v_lshl_add_u64 v[206:207], s[8:9], 0, v[184:185]
	global_load_lds_dwordx4 v[206:207], off
	s_waitcnt lgkmcnt(8)
	s_barrier
	s_waitcnt lgkmcnt(0)
	v_mfma_f32_16x16x32_bf16 v[126:129], v[130:133], v[146:149], v[126:129]
	v_mfma_f32_16x16x32_bf16 v[122:125], v[138:141], v[146:149], v[122:125]
	v_mfma_f32_16x16x32_bf16 v[114:117], v[130:133], v[186:189], v[114:117]
	v_mfma_f32_16x16x32_bf16 v[106:109], v[138:141], v[186:189], v[106:109]
	v_mfma_f32_16x16x32_bf16 v[94:97], v[130:133], v[194:197], v[94:97]
	v_mfma_f32_16x16x32_bf16 v[90:93], v[138:141], v[194:197], v[90:93]
	v_mfma_f32_16x16x32_bf16 v[82:85], v[130:133], v[202:205], v[82:85]
	v_mfma_f32_16x16x32_bf16 v[74:77], v[138:141], v[202:205], v[74:77]
	v_mfma_f32_16x16x32_bf16 v[126:129], v[134:137], v[150:153], v[126:129]
	v_mfma_f32_16x16x32_bf16 v[122:125], v[142:145], v[150:153], v[122:125]
	v_mfma_f32_16x16x32_bf16 v[114:117], v[134:137], v[190:193], v[114:117]
	v_mfma_f32_16x16x32_bf16 v[106:109], v[142:145], v[190:193], v[106:109]
	v_mfma_f32_16x16x32_bf16 v[94:97], v[134:137], v[198:201], v[94:97]
	v_mfma_f32_16x16x32_bf16 v[90:93], v[142:145], v[198:201], v[90:93]
	v_mfma_f32_16x16x32_bf16 v[82:85], v[134:137], v[216:219], v[82:85]
	v_mfma_f32_16x16x32_bf16 v[74:77], v[142:145], v[216:219], v[74:77]
	s_barrier
	s_add_i32 s19, 0, 0x14000
	s_add_i32 s26, s27, s84
	v_add_u32_e32 v162, s19, v209
	v_lshl_add_u64 v[206:207], s[46:47], 0, v[8:9]
	s_mov_b32 m0, s26
	ds_read_b128 v[220:223], v162
	ds_read_b128 v[224:227], v162 offset:1024
	ds_read_b128 v[228:231], v162 offset:2048
	ds_read_b128 v[232:235], v162 offset:3072
	global_load_lds_dwordx4 v[206:207], off
	s_add_i32 m0, s26, 0x2000
	v_lshl_add_u64 v[236:237], s[46:47], 0, v[180:181]
	global_load_lds_dwordx4 v[236:237], off
	s_barrier
	s_waitcnt lgkmcnt(0)
	v_mfma_f32_16x16x32_bf16 v[118:121], v[220:223], v[146:149], v[118:121]
	v_mfma_f32_16x16x32_bf16 v[110:113], v[228:231], v[146:149], v[110:113]
	v_mfma_f32_16x16x32_bf16 v[102:105], v[220:223], v[186:189], v[102:105]
	v_mfma_f32_16x16x32_bf16 v[98:101], v[228:231], v[186:189], v[98:101]
	v_mfma_f32_16x16x32_bf16 v[86:89], v[220:223], v[194:197], v[86:89]
	v_mfma_f32_16x16x32_bf16 v[78:81], v[228:231], v[194:197], v[78:81]
	v_mfma_f32_16x16x32_bf16 v[62:65], v[220:223], v[202:205], v[62:65]
	v_mfma_f32_16x16x32_bf16 v[58:61], v[228:231], v[202:205], v[58:61]
	v_mfma_f32_16x16x32_bf16 v[118:121], v[224:227], v[150:153], v[118:121]
	v_mfma_f32_16x16x32_bf16 v[110:113], v[232:235], v[150:153], v[110:113]
	v_mfma_f32_16x16x32_bf16 v[102:105], v[224:227], v[190:193], v[102:105]
	v_mfma_f32_16x16x32_bf16 v[98:101], v[232:235], v[190:193], v[98:101]
	v_mfma_f32_16x16x32_bf16 v[86:89], v[224:227], v[198:201], v[86:89]
	v_mfma_f32_16x16x32_bf16 v[78:81], v[232:235], v[198:201], v[78:81]
	v_mfma_f32_16x16x32_bf16 v[62:65], v[224:227], v[216:219], v[62:65]
	v_mfma_f32_16x16x32_bf16 v[58:61], v[232:235], v[216:219], v[58:61]
	s_mov_b32 m0, s85
	v_lshl_add_u64 v[238:239], s[68:69], 0, v[176:177]
	s_barrier
	ds_read_b128 v[146:149], v214 offset:16384
	ds_read_b128 v[150:153], v214 offset:17408
	ds_read_b128 v[186:189], v214 offset:18432
	ds_read_b128 v[190:193], v214 offset:19456
	ds_read_b128 v[194:197], v214 offset:20480
	ds_read_b128 v[198:201], v214 offset:21504
	ds_read_b128 v[202:205], v214 offset:22528
	ds_read_b128 v[216:219], v214 offset:23552
	global_load_lds_dwordx4 v[238:239], off
	s_mov_b32 m0, s86
	v_lshl_add_u64 v[240:241], s[68:69], 0, v[178:179]
	global_load_lds_dwordx4 v[240:241], off
	s_barrier
	s_waitcnt lgkmcnt(0)
	v_mfma_f32_16x16x32_bf16 v[70:73], v[130:133], v[146:149], v[70:73]
	v_mfma_f32_16x16x32_bf16 v[66:69], v[138:141], v[146:149], v[66:69]
	v_mfma_f32_16x16x32_bf16 v[46:49], v[130:133], v[186:189], v[46:49]
	v_mfma_f32_16x16x32_bf16 v[42:45], v[138:141], v[186:189], v[42:45]
	v_mfma_f32_16x16x32_bf16 v[30:33], v[130:133], v[194:197], v[30:33]
	v_mfma_f32_16x16x32_bf16 v[26:29], v[138:141], v[194:197], v[26:29]
	v_mfma_f32_16x16x32_bf16 v[14:17], v[130:133], v[202:205], v[14:17]
	v_mfma_f32_16x16x32_bf16 v[10:13], v[138:141], v[202:205], v[10:13]
	v_mfma_f32_16x16x32_bf16 v[70:73], v[134:137], v[150:153], v[70:73]
	v_mfma_f32_16x16x32_bf16 v[66:69], v[142:145], v[150:153], v[66:69]
	v_mfma_f32_16x16x32_bf16 v[46:49], v[134:137], v[190:193], v[46:49]
	v_mfma_f32_16x16x32_bf16 v[42:45], v[142:145], v[190:193], v[42:45]
	v_mfma_f32_16x16x32_bf16 v[30:33], v[134:137], v[198:201], v[30:33]
	v_mfma_f32_16x16x32_bf16 v[26:29], v[142:145], v[198:201], v[26:29]
	v_mfma_f32_16x16x32_bf16 v[14:17], v[134:137], v[216:219], v[14:17]
	v_mfma_f32_16x16x32_bf16 v[10:13], v[142:145], v[216:219], v[10:13]
	s_barrier
; #define PG8_STAGE(bufoff, gbase, voff) do { _Pragma("unroll") for (int _i = 0; _i < 2; ++_i) \
;         __builtin_amdgcn_global_load_lds((const unsigned*)((const char*)(gbase) + (voff)[_i]), (LAS unsigned*)(lds + (bufoff) + ldsw + _i * 8192), 16, 0, 0); } while (0)
; #define PG8_LDA(dst, b, h) do { _Pragma("unroll") for (int m = 0; m < 4; ++m) _Pragma("unroll") for (int k = 0; k < 2; ++k) dst[m][k] = *(const LAS bf16x8*)(lds + PG8_SA(b, h) + aoff + m * 2048 + k * 1024); } while (0)
; #define PG8_LDB(dst, b, h) do { _Pragma("unroll") for (int n = 0; n < 2; ++n) _Pragma("unroll") for (int k = 0; k < 2; ++k) dst[n][k] = *(const LAS bf16x8*)(lds + PG8_SB(b, h) + boff + n * 2048 + k * 1024); } while (0)
; #define PG8_MMA(ai, bj, At, Bt) do { __builtin_amdgcn_s_setprio(1); _Pragma("unroll") for (int m = 0; m < 4; ++m) _Pragma("unroll") for (int n = 0; n < 2; ++n) _Pragma("unroll") for (int k = 0; k < 2; ++k) \
;         acc[ai][bj][m][n] = __builtin_amdgcn_mfma_f32_16x16x32_bf16(Bt[n][k], At[m][k], acc[ai][bj][m][n], 0, 0, 0); __builtin_amdgcn_s_setprio(0); } while (0)
; #define PG8_WAIT_V(n) asm volatile("s_waitcnt vmcnt(" #n ")" ::: "memory")
; #define PG8_WAIT_L(n) asm volatile("s_waitcnt lgkmcnt(" #n ")" ::: "memory")
; #define PG8_BAR __builtin_amdgcn_s_barrier()
; #define PG8_SCHED __builtin_amdgcn_sched_barrier(0)
; template <class Epi>
; DEVI void gemm_phase(LAS unsigned char* lds, const Gemm g, const Epi& E) {
;     ...
;             PG8_STAGE(PG8_SB(0, 1), b2 + hstepB, voffB);
;             PG8_WAIT_V(6); PG8_BAR; PG8_MMA(1, 1, At, B1); PG8_BAR;
;             PG8_LDB(B0, 1, 0); PG8_SCHED; PG8_LDA(At, 1, 0); PG8_STAGE(PG8_SA(0, 1), a2 + hstepA, voffA);
;             PG8_WAIT_L(8); PG8_BAR; PG8_WAIT_L(0); PG8_MMA(0, 0, At, B0); PG8_BAR; PG8_SCHED;
;             PG8_LDB(B1, 1, 1); PG8_STAGE(PG8_SB(1, 0), b3, voffB);
;             PG8_BAR; PG8_WAIT_L(0); PG8_MMA(0, 1, At, B1); PG8_BAR;
;             PG8_LDA(At, 1, 1); PG8_STAGE(PG8_SA(1, 0), a3, voffA);
;             PG8_BAR; PG8_WAIT_L(0); PG8_MMA(1, 0, At, B0); PG8_BAR; PG8_SCHED;
	s_add_u32 s26, s46, 0x40000
	s_addc_u32 s27, s47, 0
	s_add_i32 s19, s19, s84
	s_mov_b32 m0, s19
	v_lshl_add_u64 v[130:131], s[26:27], 0, v[8:9]
	global_load_lds_dwordx4 v[130:131], off
	s_add_i32 m0, s19, 0x2000
	v_lshl_add_u64 v[130:131], s[26:27], 0, v[180:181]
	global_load_lds_dwordx4 v[130:131], off
	s_waitcnt vmcnt(6)
	s_barrier
	v_mfma_f32_16x16x32_bf16 v[50:53], v[220:223], v[146:149], v[50:53]
	v_mfma_f32_16x16x32_bf16 v[54:57], v[228:231], v[146:149], v[54:57]
	v_mfma_f32_16x16x32_bf16 v[34:37], v[220:223], v[186:189], v[34:37]
	v_mfma_f32_16x16x32_bf16 v[38:41], v[228:231], v[186:189], v[38:41]
	v_mfma_f32_16x16x32_bf16 v[18:21], v[220:223], v[194:197], v[18:21]
	v_mfma_f32_16x16x32_bf16 v[22:25], v[228:231], v[194:197], v[22:25]
	v_mfma_f32_16x16x32_bf16 v[0:3], v[220:223], v[202:205], v[0:3]
	v_mfma_f32_16x16x32_bf16 v[4:7], v[228:231], v[202:205], v[4:7]
	v_mfma_f32_16x16x32_bf16 v[50:53], v[224:227], v[150:153], v[50:53]
	v_mfma_f32_16x16x32_bf16 v[54:57], v[232:235], v[150:153], v[54:57]
	v_mfma_f32_16x16x32_bf16 v[34:37], v[224:227], v[190:193], v[34:37]
	v_mfma_f32_16x16x32_bf16 v[38:41], v[232:235], v[190:193], v[38:41]
	v_mfma_f32_16x16x32_bf16 v[18:21], v[224:227], v[198:201], v[18:21]
	v_mfma_f32_16x16x32_bf16 v[22:25], v[232:235], v[198:201], v[22:25]
	v_mfma_f32_16x16x32_bf16 v[0:3], v[224:227], v[216:219], v[0:3]
	v_mfma_f32_16x16x32_bf16 v[4:7], v[232:235], v[216:219], v[4:7]
	s_add_i32 s19, 0, 0x18000
	v_add_u32_e32 v142, s19, v209
	s_barrier
	ds_read_b128 v[130:133], v142
	ds_read_b128 v[134:137], v142 offset:1024
	ds_read_b128 v[138:141], v142 offset:2048
	ds_read_b128 v[142:145], v142 offset:3072
	s_add_u32 s26, s68, 0x40000
	s_addc_u32 s27, s69, 0
	s_mov_b32 m0, s87
	v_lshl_add_u64 v[220:221], s[26:27], 0, v[176:177]
	ds_read_b128 v[146:149], v214 offset:32768
	ds_read_b128 v[150:153], v214 offset:33792
	ds_read_b128 v[186:189], v214 offset:34816
	ds_read_b128 v[190:193], v214 offset:35840
	ds_read_b128 v[194:197], v214 offset:36864
	ds_read_b128 v[198:201], v214 offset:37888
	ds_read_b128 v[202:205], v214 offset:38912
	ds_read_b128 v[216:219], v214 offset:39936
	global_load_lds_dwordx4 v[220:221], off
	s_mov_b32 m0, s88
	v_lshl_add_u64 v[220:221], s[26:27], 0, v[178:179]
	global_load_lds_dwordx4 v[220:221], off
	s_waitcnt lgkmcnt(8)
	s_barrier
	s_waitcnt lgkmcnt(0)
	v_mfma_f32_16x16x32_bf16 v[126:129], v[130:133], v[146:149], v[126:129]
	v_mfma_f32_16x16x32_bf16 v[122:125], v[138:141], v[146:149], v[122:125]
	v_mfma_f32_16x16x32_bf16 v[114:117], v[130:133], v[186:189], v[114:117]
	v_mfma_f32_16x16x32_bf16 v[106:109], v[138:141], v[186:189], v[106:109]
	v_mfma_f32_16x16x32_bf16 v[94:97], v[130:133], v[194:197], v[94:97]
	v_mfma_f32_16x16x32_bf16 v[90:93], v[138:141], v[194:197], v[90:93]
	v_mfma_f32_16x16x32_bf16 v[82:85], v[130:133], v[202:205], v[82:85]
	v_mfma_f32_16x16x32_bf16 v[74:77], v[138:141], v[202:205], v[74:77]
	v_mfma_f32_16x16x32_bf16 v[126:129], v[134:137], v[150:153], v[126:129]
	v_mfma_f32_16x16x32_bf16 v[122:125], v[142:145], v[150:153], v[122:125]
	v_mfma_f32_16x16x32_bf16 v[114:117], v[134:137], v[190:193], v[114:117]
	v_mfma_f32_16x16x32_bf16 v[106:109], v[142:145], v[190:193], v[106:109]
	v_mfma_f32_16x16x32_bf16 v[94:97], v[134:137], v[198:201], v[94:97]
	v_mfma_f32_16x16x32_bf16 v[90:93], v[142:145], v[198:201], v[90:93]
	v_mfma_f32_16x16x32_bf16 v[82:85], v[134:137], v[216:219], v[82:85]
	v_mfma_f32_16x16x32_bf16 v[74:77], v[142:145], v[216:219], v[74:77]
	s_barrier
	s_add_i32 s38, 0, 0x1c000
	s_add_i32 s19, s19, s84
	v_add_u32_e32 v162, s38, v209
	v_lshl_add_u64 v[206:207], v[206:207], 0, s[70:71]
	s_mov_b32 m0, s19
	ds_read_b128 v[220:223], v162
	ds_read_b128 v[224:227], v162 offset:1024
	ds_read_b128 v[228:231], v162 offset:2048
	ds_read_b128 v[232:235], v162 offset:3072
	global_load_lds_dwordx4 v[206:207], off
	s_add_i32 m0, s19, 0x2000
	v_lshl_add_u64 v[206:207], v[236:237], 0, s[70:71]
	global_load_lds_dwordx4 v[206:207], off
	s_barrier
	s_waitcnt lgkmcnt(0)
	v_mfma_f32_16x16x32_bf16 v[118:121], v[220:223], v[146:149], v[118:121]
	v_mfma_f32_16x16x32_bf16 v[110:113], v[228:231], v[146:149], v[110:113]
	v_mfma_f32_16x16x32_bf16 v[102:105], v[220:223], v[186:189], v[102:105]
	v_mfma_f32_16x16x32_bf16 v[98:101], v[228:231], v[186:189], v[98:101]
	v_mfma_f32_16x16x32_bf16 v[86:89], v[220:223], v[194:197], v[86:89]
	v_mfma_f32_16x16x32_bf16 v[78:81], v[228:231], v[194:197], v[78:81]
	v_mfma_f32_16x16x32_bf16 v[62:65], v[220:223], v[202:205], v[62:65]
	v_mfma_f32_16x16x32_bf16 v[58:61], v[228:231], v[202:205], v[58:61]
	v_mfma_f32_16x16x32_bf16 v[118:121], v[224:227], v[150:153], v[118:121]
	v_mfma_f32_16x16x32_bf16 v[110:113], v[232:235], v[150:153], v[110:113]
	v_mfma_f32_16x16x32_bf16 v[102:105], v[224:227], v[190:193], v[102:105]
	v_mfma_f32_16x16x32_bf16 v[98:101], v[232:235], v[190:193], v[98:101]
	v_mfma_f32_16x16x32_bf16 v[86:89], v[224:227], v[198:201], v[86:89]
	v_mfma_f32_16x16x32_bf16 v[78:81], v[232:235], v[198:201], v[78:81]
	v_mfma_f32_16x16x32_bf16 v[62:65], v[224:227], v[216:219], v[62:65]
	v_mfma_f32_16x16x32_bf16 v[58:61], v[232:235], v[216:219], v[58:61]
	s_mov_b32 m0, s89
	v_lshl_add_u64 v[206:207], v[238:239], 0, s[70:71]
	s_barrier
	ds_read_b128 v[146:149], v214 offset:49152
	ds_read_b128 v[150:153], v214 offset:50176
	ds_read_b128 v[186:189], v214 offset:51200
	ds_read_b128 v[190:193], v214 offset:52224
	ds_read_b128 v[194:197], v214 offset:53248
	ds_read_b128 v[198:201], v214 offset:54272
	ds_read_b128 v[202:205], v214 offset:55296
	ds_read_b128 v[216:219], v214 offset:56320
	global_load_lds_dwordx4 v[206:207], off
	s_mov_b32 m0, s90
	v_lshl_add_u64 v[206:207], v[240:241], 0, s[70:71]
	global_load_lds_dwordx4 v[206:207], off
	s_barrier
; #define PG8_STAGE(bufoff, gbase, voff) do { _Pragma("unroll") for (int _i = 0; _i < 2; ++_i) \
;         __builtin_amdgcn_global_load_lds((const unsigned*)((const char*)(gbase) + (voff)[_i]), (LAS unsigned*)(lds + (bufoff) + ldsw + _i * 8192), 16, 0, 0); } while (0)
; #define PG8_MMA(ai, bj, At, Bt) do { __builtin_amdgcn_s_setprio(1); _Pragma("unroll") for (int m = 0; m < 4; ++m) _Pragma("unroll") for (int n = 0; n < 2; ++n) _Pragma("unroll") for (int k = 0; k < 2; ++k) \
;         acc[ai][bj][m][n] = __builtin_amdgcn_mfma_f32_16x16x32_bf16(Bt[n][k], At[m][k], acc[ai][bj][m][n], 0, 0, 0); __builtin_amdgcn_s_setprio(0); } while (0)
; #define PG8_WAIT_V(n) asm volatile("s_waitcnt vmcnt(" #n ")" ::: "memory")
; #define PG8_WAIT_L(n) asm volatile("s_waitcnt lgkmcnt(" #n ")" ::: "memory")
; #define PG8_BAR __builtin_amdgcn_s_barrier()
; #define PG8_SCHED __builtin_amdgcn_sched_barrier(0)
; template <class Epi>
; DEVI void gemm_phase(LAS unsigned char* lds, const Gemm g, const Epi& E) {
;     ...
;             PG8_BAR; PG8_WAIT_L(0); PG8_MMA(1, 0, At, B0); PG8_BAR; PG8_SCHED;
;             PG8_STAGE(PG8_SB(1, 1), b3 + hstepB, voffB);
;             PG8_WAIT_V(6); PG8_BAR; PG8_MMA(1, 1, At, B1); PG8_BAR;
;         }
;         {
;             const int row0 = cur.pm * BM + wr * 64 + fr, col0 = cur.pn * BM + wc * 32 + (Epi::PERM ? 8 : 4) * fq; constexpr int NST = Epi::PERM ? 4 : 16;
;             float rsv[8];
;             if constexpr (Epi::RS) { f32x4 q4[8];
; #pragma unroll
;                 for (int i = 0; i < 8; ++i) q4[i] = *(const f32x4*)(E.ssq_in + (size_t)(row0 + (i >> 2) * HALF + (i & 3) * 16) * 4);
; #pragma unroll
;                 for (int i = 0; i < 8; ++i) rsv[i] = rsqrtf((((q4[i][0] + q4[i][1]) + q4[i][2]) + q4[i][3]) * (1.f / DM) + 1e-6f); }
	s_waitcnt lgkmcnt(0)
	v_mfma_f32_16x16x32_bf16 v[70:73], v[130:133], v[146:149], v[70:73]
	v_mfma_f32_16x16x32_bf16 v[66:69], v[138:141], v[146:149], v[66:69]
	v_mfma_f32_16x16x32_bf16 v[46:49], v[130:133], v[186:189], v[46:49]
	v_mfma_f32_16x16x32_bf16 v[42:45], v[138:141], v[186:189], v[42:45]
	v_mfma_f32_16x16x32_bf16 v[30:33], v[130:133], v[194:197], v[30:33]
	v_mfma_f32_16x16x32_bf16 v[26:29], v[138:141], v[194:197], v[26:29]
	v_mfma_f32_16x16x32_bf16 v[14:17], v[130:133], v[202:205], v[14:17]
	v_mfma_f32_16x16x32_bf16 v[10:13], v[138:141], v[202:205], v[10:13]
	v_mfma_f32_16x16x32_bf16 v[70:73], v[134:137], v[150:153], v[70:73]
	v_mfma_f32_16x16x32_bf16 v[66:69], v[142:145], v[150:153], v[66:69]
	v_mfma_f32_16x16x32_bf16 v[46:49], v[134:137], v[190:193], v[46:49]
	v_mfma_f32_16x16x32_bf16 v[42:45], v[142:145], v[190:193], v[42:45]
	v_mfma_f32_16x16x32_bf16 v[30:33], v[134:137], v[198:201], v[30:33]
	v_mfma_f32_16x16x32_bf16 v[26:29], v[142:145], v[198:201], v[26:29]
	v_mfma_f32_16x16x32_bf16 v[14:17], v[134:137], v[216:219], v[14:17]
	v_mfma_f32_16x16x32_bf16 v[10:13], v[142:145], v[216:219], v[10:13]
	s_barrier
	s_add_u32 s26, s46, 0x40080
	s_addc_u32 s27, s47, 0
	s_add_i32 s19, s38, s84
	s_mov_b32 m0, s19
	v_lshl_add_u64 v[130:131], s[26:27], 0, v[8:9]
	global_load_lds_dwordx4 v[130:131], off
	s_add_i32 m0, s19, 0x2000
	v_lshl_add_u64 v[130:131], s[26:27], 0, v[180:181]
	global_load_lds_dwordx4 v[130:131], off
	s_waitcnt vmcnt(6)
	s_barrier
	v_mfma_f32_16x16x32_bf16 v[50:53], v[220:223], v[146:149], v[50:53]
	v_mfma_f32_16x16x32_bf16 v[54:57], v[228:231], v[146:149], v[54:57]
	v_mfma_f32_16x16x32_bf16 v[34:37], v[220:223], v[186:189], v[34:37]
	v_mfma_f32_16x16x32_bf16 v[38:41], v[228:231], v[186:189], v[38:41]
	v_mfma_f32_16x16x32_bf16 v[18:21], v[220:223], v[194:197], v[18:21]
	v_mfma_f32_16x16x32_bf16 v[22:25], v[228:231], v[194:197], v[22:25]
	v_mfma_f32_16x16x32_bf16 v[0:3], v[220:223], v[202:205], v[0:3]
	v_mfma_f32_16x16x32_bf16 v[4:7], v[228:231], v[202:205], v[4:7]
	v_mfma_f32_16x16x32_bf16 v[50:53], v[224:227], v[150:153], v[50:53]
	v_mfma_f32_16x16x32_bf16 v[54:57], v[232:235], v[150:153], v[54:57]
	v_mfma_f32_16x16x32_bf16 v[34:37], v[224:227], v[190:193], v[34:37]
	v_mfma_f32_16x16x32_bf16 v[38:41], v[232:235], v[190:193], v[38:41]
	v_mfma_f32_16x16x32_bf16 v[18:21], v[224:227], v[198:201], v[18:21]
	v_mfma_f32_16x16x32_bf16 v[22:25], v[232:235], v[198:201], v[22:25]
	v_mfma_f32_16x16x32_bf16 v[0:3], v[224:227], v[216:219], v[0:3]
	v_mfma_f32_16x16x32_bf16 v[4:7], v[232:235], v[216:219], v[4:7]
	s_add_i32 s18, s18, 2
	s_add_u32 s8, s8, 0x100
	s_addc_u32 s9, s9, 0
	s_add_u32 s11, s11, 0x100
	s_addc_u32 s13, s13, 0
	s_cmp_gt_u32 s18, 13
	s_barrier
	s_cbranch_scc0 .LBB0_356
	s_setprio 0
	v_lshl_add_u32 v202, s6, 8, v208
	v_ashrrev_i32_e32 v203, 31, v202
	v_or_b32_e32 v200, 16, v202
	v_lshl_add_u64 v[130:131], v[202:203], 4, s[76:77]
	v_ashrrev_i32_e32 v201, 31, v200
	v_lshl_add_u64 v[132:133], v[200:201], 4, s[76:77]
	global_load_dwordx4 v[204:207], v[130:131], off
	global_load_dwordx4 v[216:219], v[132:133], off
	v_or_b32_e32 v198, 32, v202
	v_ashrrev_i32_e32 v199, 31, v198
	v_or_b32_e32 v196, 48, v202
	v_add_u32_e32 v194, 0x80, v202
	v_lshl_add_u64 v[130:131], v[198:199], 4, s[76:77]
	v_ashrrev_i32_e32 v197, 31, v196
	v_ashrrev_i32_e32 v195, 31, v194
	v_add_u32_e32 v192, 0x90, v202
	v_add_u32_e32 v190, 0xa0, v202
	v_add_u32_e32 v188, 0xb0, v202
	v_lshl_add_u64 v[132:133], v[196:197], 4, s[76:77]
	global_load_dwordx4 v[146:149], v[130:131], off
	global_load_dwordx4 v[150:153], v[132:133], off
	v_lshl_add_u64 v[130:131], v[194:195], 4, s[76:77]
	v_ashrrev_i32_e32 v193, 31, v192
	v_ashrrev_i32_e32 v191, 31, v190
	v_ashrrev_i32_e32 v189, 31, v188
	v_lshl_add_u64 v[132:133], v[192:193], 4, s[76:77]
	global_load_dwordx4 v[138:141], v[130:131], off
	global_load_dwordx4 v[142:145], v[132:133], off
	v_lshl_add_u64 v[130:131], v[190:191], 4, s[76:77]
	v_lshl_add_u64 v[134:135], v[188:189], 4, s[76:77]
	global_load_dwordx4 v[130:133], v[130:131], off
	s_nop 0
	global_load_dwordx4 v[134:137], v[134:135], off
	s_waitcnt vmcnt(0)
	v_mov_b32_e32 v187, v204
	v_mov_b32_e32 v186, v216
	v_mov_b32_e32 v204, v217
	v_mov_b32_e32 v221, v206
	v_mov_b32_e32 v220, v218
	v_pk_add_f32 v[186:187], v[186:187], v[204:205]
	v_mov_b32_e32 v206, v219
	v_pk_add_f32 v[186:187], v[220:221], v[186:187]
	s_nop 0
	v_pk_add_f32 v[186:187], v[206:207], v[186:187]
	s_nop 0
	v_pk_fma_f32 v[204:205], v[186:187], s[72:73], v[160:161] op_sel_hi:[1,0,0]
	v_lshl_or_b32 v186, s4, 8, v213
	v_mul_f32_e32 v162, 0x4b800000, v205
	v_cmp_gt_f32_e32 vcc, s94, v205
	v_cmp_gt_f32_e64 s[6:7], s94, v204
	s_nop 0
	v_cndmask_b32_e32 v162, v205, v162, vcc
	v_rsq_f32_e32 v162, v162
	s_nop 0
	v_mul_f32_e32 v163, 0x45800000, v162
	v_cndmask_b32_e32 v206, v162, v163, vcc
	v_pk_mul_f32 v[128:129], v[128:129], v[206:207] op_sel_hi:[1,0]
	v_pk_mul_f32 v[126:127], v[126:127], v[206:207] op_sel_hi:[1,0]
	v_pk_mul_f32 v[124:125], v[124:125], v[206:207] op_sel_hi:[1,0]
	v_pk_mul_f32 v[122:123], v[122:123], v[206:207] op_sel_hi:[1,0]
	v_cmp_lt_i32_e32 vcc, s52, v186
	s_and_saveexec_b64 s[0:1], vcc
	s_xor_b64 s[8:9], exec, s[0:1]
	s_cbranch_execz .LBB0_361
	v_cmp_eq_u32_e64 s[4:5], s53, v186
	s_and_saveexec_b64 s[46:47], s[4:5]
	s_cbranch_execz .LBB0_360
	v_lshlrev_b64 v[216:217], 6, v[202:203]
	v_lshl_add_u64 v[216:217], s[58:59], 0, v[216:217]
	global_store_dwordx4 v[216:217], v[126:129], off
	global_store_dwordx4 v[216:217], v[122:125], off offset:16
